# EpiResid epilogues (W_out + FFN-down) rewritten by hand: 16 XB loads in flight with counted vmcnt, batched SSQ reductions
# baseline (speedup 1.0000x reference)
.LBB0_125:
	v_and_b32_e32 v141, 64, v217
	v_xor_b32_e32 v140, 16, v217
	v_add_u32_e32 v141, 64, v141
	s_lshl_b32 s16, s66, 8
	v_cmp_lt_i32_e32 vcc, v140, v141
	s_add_i32 s16, s16, s79
	v_mbcnt_lo_u32_b32 v136, -1, 0
	v_mbcnt_hi_u32_b32 v136, -1, v136
	s_nop 0
	v_cndmask_b32_e32 v140, v217, v140, vcc
	v_and_or_b32 v138, v136, 15, s16
	s_lshl_b32 s16, s64, 8
	v_lshlrev_b32_e32 v145, 2, v140
	v_xor_b32_e32 v140, 32, v217
	v_bfe_u32 v139, v136, 4, 2
	s_or_b32 s16, s16, s80
	v_cmp_lt_i32_e32 vcc, v140, v141
	v_lshl_or_b32 v136, v139, 3, s16
	v_ashrrev_i32_e32 v137, 31, v136
	s_nop 0
	v_cndmask_b32_e32 v140, v217, v140, vcc
	v_cmp_eq_u32_e32 vcc, 0, v139
	v_ashrrev_i32_e32 v139, 31, v138
	v_lshlrev_b32_e32 v144, 2, v140
	v_lshlrev_b64 v[140:141], 11, v[138:139]
	v_lshl_add_u64 v[140:141], s[10:11], 0, v[140:141]
	v_lshl_add_u64 v[224:225], v[136:137], 1, v[140:141]
	s_lshl_b32 s64, s64, 2
	s_ashr_i32 s65, s64, 31
	s_mov_b32 s101, 0
	v_lshlrev_b64 v[140:141], 6, v[138:139]
	v_lshl_add_u64 v[140:141], s[22:23], 0, v[140:141]
	v_lshl_add_u64 v[140:141], s[64:65], 2, v[140:141]
	s_lshl_b32 s20, s78, 2
	v_lshl_add_u64 v[140:141], v[140:141], 0, s[20:21]
	s_mov_b32 s100, 0x2000
	v_lshl_add_u64 v[252:253], s[100:101], 0, v[140:141]
	global_load_dwordx4 v[154:157], v[224:225], off
	global_load_dwordx4 v[158:161], v[224:225], off offset:256
	s_mov_b32 s100, 0x8000
	v_lshl_add_u64 v[226:227], s[100:101], 0, v[224:225]
	global_load_dwordx4 v[162:165], v[226:227], off
	global_load_dwordx4 v[166:169], v[226:227], off offset:256
	s_mov_b32 s100, 0x8000
	v_lshl_add_u64 v[228:229], s[100:101], 0, v[226:227]
	global_load_dwordx4 v[170:173], v[228:229], off
	global_load_dwordx4 v[174:177], v[228:229], off offset:256
	s_mov_b32 s100, 0x8000
	v_lshl_add_u64 v[230:231], s[100:101], 0, v[228:229]
	global_load_dwordx4 v[178:181], v[230:231], off
	global_load_dwordx4 v[182:185], v[230:231], off offset:256
	s_mov_b32 s100, 0x28000
	v_lshl_add_u64 v[232:233], s[100:101], 0, v[230:231]
	global_load_dwordx4 v[186:189], v[232:233], off
	global_load_dwordx4 v[190:193], v[232:233], off offset:256
	s_mov_b32 s100, 0x8000
	v_lshl_add_u64 v[234:235], s[100:101], 0, v[232:233]
	global_load_dwordx4 v[194:197], v[234:235], off
	global_load_dwordx4 v[198:201], v[234:235], off offset:256
	s_mov_b32 s100, 0x8000
	v_lshl_add_u64 v[236:237], s[100:101], 0, v[234:235]
	global_load_dwordx4 v[202:205], v[236:237], off
	global_load_dwordx4 v[206:209], v[236:237], off offset:256
	s_mov_b32 s100, 0x8000
	v_lshl_add_u64 v[238:239], s[100:101], 0, v[236:237]
	global_load_dwordx4 v[210:213], v[238:239], off
	global_load_dwordx4 v[220:223], v[238:239], off offset:256
	s_waitcnt vmcnt(15)
	v_lshlrev_b32_e32 v146, 16, v154
	v_and_b32_e32 v147, 0xffff0000, v154
	v_lshlrev_b32_e32 v148, 16, v155
	v_and_b32_e32 v149, 0xffff0000, v155
	v_lshlrev_b32_e32 v150, 16, v156
	v_and_b32_e32 v151, 0xffff0000, v156
	v_lshlrev_b32_e32 v152, 16, v157
	v_and_b32_e32 v153, 0xffff0000, v157
	v_pk_add_f32 v[128:129], v[128:129], v[148:149]
	v_pk_add_f32 v[126:127], v[126:127], v[146:147]
	v_pk_add_f32 v[124:125], v[124:125], v[152:153]
	v_pk_add_f32 v[122:123], v[122:123], v[150:151]
	v_cvt_pk_bf16_f32 v136, v126, v127
	v_cvt_pk_bf16_f32 v137, v128, v129
	v_cvt_pk_bf16_f32 v138, v122, v123
	v_cvt_pk_bf16_f32 v139, v124, v125
	global_store_dwordx4 v[224:225], v[136:139], off
	v_mul_f32_e32 v146, v127, v127
	v_mul_f32_e32 v147, v129, v129
	v_fmac_f32_e32 v146, v126, v126
	v_fmac_f32_e32 v147, v128, v128
	v_add_f32_e32 v146, v146, v147
	v_mul_f32_e32 v147, v123, v123
	v_mul_f32_e32 v148, v125, v125
	v_fmac_f32_e32 v147, v122, v122
	v_fmac_f32_e32 v148, v124, v124
	v_add_f32_e32 v147, v147, v148
	v_add_f32_e32 v240, v146, v147
	s_waitcnt vmcnt(15)
	v_lshlrev_b32_e32 v146, 16, v158
	v_and_b32_e32 v147, 0xffff0000, v158
	v_lshlrev_b32_e32 v148, 16, v159
	v_and_b32_e32 v149, 0xffff0000, v159
	v_lshlrev_b32_e32 v150, 16, v160
	v_and_b32_e32 v151, 0xffff0000, v160
	v_lshlrev_b32_e32 v152, 16, v161
	v_and_b32_e32 v153, 0xffff0000, v161
	v_pk_add_f32 v[120:121], v[120:121], v[148:149]
	v_pk_add_f32 v[118:119], v[118:119], v[146:147]
	v_pk_add_f32 v[116:117], v[116:117], v[152:153]
	v_pk_add_f32 v[114:115], v[114:115], v[150:151]
	v_cvt_pk_bf16_f32 v248, v118, v119
	v_cvt_pk_bf16_f32 v249, v120, v121
	v_cvt_pk_bf16_f32 v250, v114, v115
	v_cvt_pk_bf16_f32 v251, v116, v117
	global_store_dwordx4 v[224:225], v[248:251], off offset:256
	v_mul_f32_e32 v146, v119, v119
	v_mul_f32_e32 v147, v121, v121
	v_fmac_f32_e32 v146, v118, v118
	v_fmac_f32_e32 v147, v120, v120
	v_add_f32_e32 v146, v146, v147
	v_mul_f32_e32 v147, v115, v115
	v_mul_f32_e32 v148, v117, v117
	v_fmac_f32_e32 v147, v114, v114
	v_fmac_f32_e32 v148, v116, v116
	v_add_f32_e32 v147, v147, v148
	v_add_f32_e32 v146, v146, v147
	v_add_f32_e32 v240, v240, v146
	s_waitcnt vmcnt(15)
	v_lshlrev_b32_e32 v146, 16, v162
	v_and_b32_e32 v147, 0xffff0000, v162
	v_lshlrev_b32_e32 v148, 16, v163
	v_and_b32_e32 v149, 0xffff0000, v163
	v_lshlrev_b32_e32 v150, 16, v164
	v_and_b32_e32 v151, 0xffff0000, v164
	v_lshlrev_b32_e32 v152, 16, v165
	v_and_b32_e32 v153, 0xffff0000, v165
	v_pk_add_f32 v[112:113], v[112:113], v[148:149]
	v_pk_add_f32 v[110:111], v[110:111], v[146:147]
	v_pk_add_f32 v[108:109], v[108:109], v[152:153]
	v_pk_add_f32 v[106:107], v[106:107], v[150:151]
	v_cvt_pk_bf16_f32 v136, v110, v111
	v_cvt_pk_bf16_f32 v137, v112, v113
	v_cvt_pk_bf16_f32 v138, v106, v107
	v_cvt_pk_bf16_f32 v139, v108, v109
	global_store_dwordx4 v[226:227], v[136:139], off
	v_mul_f32_e32 v146, v111, v111
	v_mul_f32_e32 v147, v113, v113
	v_fmac_f32_e32 v146, v110, v110
	v_fmac_f32_e32 v147, v112, v112
	v_add_f32_e32 v146, v146, v147
	v_mul_f32_e32 v147, v107, v107
	v_mul_f32_e32 v148, v109, v109
	v_fmac_f32_e32 v147, v106, v106
	v_fmac_f32_e32 v148, v108, v108
	v_add_f32_e32 v147, v147, v148
	v_add_f32_e32 v241, v146, v147
	s_waitcnt vmcnt(15)
	v_lshlrev_b32_e32 v146, 16, v166
	v_and_b32_e32 v147, 0xffff0000, v166
	v_lshlrev_b32_e32 v148, 16, v167
	v_and_b32_e32 v149, 0xffff0000, v167
	v_lshlrev_b32_e32 v150, 16, v168
	v_and_b32_e32 v151, 0xffff0000, v168
	v_lshlrev_b32_e32 v152, 16, v169
	v_and_b32_e32 v153, 0xffff0000, v169
	v_pk_add_f32 v[104:105], v[104:105], v[148:149]
	v_pk_add_f32 v[102:103], v[102:103], v[146:147]
	v_pk_add_f32 v[100:101], v[100:101], v[152:153]
	v_pk_add_f32 v[98:99], v[98:99], v[150:151]
	v_cvt_pk_bf16_f32 v248, v102, v103
	v_cvt_pk_bf16_f32 v249, v104, v105
	v_cvt_pk_bf16_f32 v250, v98, v99
	v_cvt_pk_bf16_f32 v251, v100, v101
	global_store_dwordx4 v[226:227], v[248:251], off offset:256
	v_mul_f32_e32 v146, v103, v103
	v_mul_f32_e32 v147, v105, v105
	v_fmac_f32_e32 v146, v102, v102
	v_fmac_f32_e32 v147, v104, v104
	v_add_f32_e32 v146, v146, v147
	v_mul_f32_e32 v147, v99, v99
	v_mul_f32_e32 v148, v101, v101
	v_fmac_f32_e32 v147, v98, v98
	v_fmac_f32_e32 v148, v100, v100
	v_add_f32_e32 v147, v147, v148
	v_add_f32_e32 v146, v146, v147
	v_add_f32_e32 v241, v241, v146
	s_waitcnt vmcnt(15)
	v_lshlrev_b32_e32 v146, 16, v170
	v_and_b32_e32 v147, 0xffff0000, v170
	v_lshlrev_b32_e32 v148, 16, v171
	v_and_b32_e32 v149, 0xffff0000, v171
	v_lshlrev_b32_e32 v150, 16, v172
	v_and_b32_e32 v151, 0xffff0000, v172
	v_lshlrev_b32_e32 v152, 16, v173
	v_and_b32_e32 v153, 0xffff0000, v173
	v_pk_add_f32 v[94:95], v[94:95], v[148:149]
	v_pk_add_f32 v[92:93], v[92:93], v[146:147]
	v_pk_add_f32 v[90:91], v[90:91], v[152:153]
	v_pk_add_f32 v[88:89], v[88:89], v[150:151]
	v_cvt_pk_bf16_f32 v136, v92, v93
	v_cvt_pk_bf16_f32 v137, v94, v95
	v_cvt_pk_bf16_f32 v138, v88, v89
	v_cvt_pk_bf16_f32 v139, v90, v91
	global_store_dwordx4 v[228:229], v[136:139], off
	v_mul_f32_e32 v146, v93, v93
	v_mul_f32_e32 v147, v95, v95
	v_fmac_f32_e32 v146, v92, v92
	v_fmac_f32_e32 v147, v94, v94
	v_add_f32_e32 v146, v146, v147
	v_mul_f32_e32 v147, v89, v89
	v_mul_f32_e32 v148, v91, v91
	v_fmac_f32_e32 v147, v88, v88
	v_fmac_f32_e32 v148, v90, v90
	v_add_f32_e32 v147, v147, v148
	v_add_f32_e32 v242, v146, v147
	s_waitcnt vmcnt(15)
	v_lshlrev_b32_e32 v146, 16, v174
	v_and_b32_e32 v147, 0xffff0000, v174
	v_lshlrev_b32_e32 v148, 16, v175
	v_and_b32_e32 v149, 0xffff0000, v175
	v_lshlrev_b32_e32 v150, 16, v176
	v_and_b32_e32 v151, 0xffff0000, v176
	v_lshlrev_b32_e32 v152, 16, v177
	v_and_b32_e32 v153, 0xffff0000, v177
	v_pk_add_f32 v[86:87], v[86:87], v[148:149]
	v_pk_add_f32 v[84:85], v[84:85], v[146:147]
	v_pk_add_f32 v[82:83], v[82:83], v[152:153]
	v_pk_add_f32 v[80:81], v[80:81], v[150:151]
	v_cvt_pk_bf16_f32 v248, v84, v85
	v_cvt_pk_bf16_f32 v249, v86, v87
	v_cvt_pk_bf16_f32 v250, v80, v81
	v_cvt_pk_bf16_f32 v251, v82, v83
	global_store_dwordx4 v[228:229], v[248:251], off offset:256
	v_mul_f32_e32 v146, v85, v85
	v_mul_f32_e32 v147, v87, v87
	v_fmac_f32_e32 v146, v84, v84
	v_fmac_f32_e32 v147, v86, v86
	v_add_f32_e32 v146, v146, v147
	v_mul_f32_e32 v147, v81, v81
	v_mul_f32_e32 v148, v83, v83
	v_fmac_f32_e32 v147, v80, v80
	v_fmac_f32_e32 v148, v82, v82
	v_add_f32_e32 v147, v147, v148
	v_add_f32_e32 v146, v146, v147
	v_add_f32_e32 v242, v242, v146
	s_waitcnt vmcnt(15)
	v_lshlrev_b32_e32 v146, 16, v178
	v_and_b32_e32 v147, 0xffff0000, v178
	v_lshlrev_b32_e32 v148, 16, v179
	v_and_b32_e32 v149, 0xffff0000, v179
	v_lshlrev_b32_e32 v150, 16, v180
	v_and_b32_e32 v151, 0xffff0000, v180
	v_lshlrev_b32_e32 v152, 16, v181
	v_and_b32_e32 v153, 0xffff0000, v181
	v_pk_add_f32 v[78:79], v[78:79], v[148:149]
	v_pk_add_f32 v[76:77], v[76:77], v[146:147]
	v_pk_add_f32 v[74:75], v[74:75], v[152:153]
	v_pk_add_f32 v[72:73], v[72:73], v[150:151]
	v_cvt_pk_bf16_f32 v136, v76, v77
	v_cvt_pk_bf16_f32 v137, v78, v79
	v_cvt_pk_bf16_f32 v138, v72, v73
	v_cvt_pk_bf16_f32 v139, v74, v75
	global_store_dwordx4 v[230:231], v[136:139], off
	v_mul_f32_e32 v146, v77, v77
	v_mul_f32_e32 v147, v79, v79
	v_fmac_f32_e32 v146, v76, v76
	v_fmac_f32_e32 v147, v78, v78
	v_add_f32_e32 v146, v146, v147
	v_mul_f32_e32 v147, v73, v73
	v_mul_f32_e32 v148, v75, v75
	v_fmac_f32_e32 v147, v72, v72
	v_fmac_f32_e32 v148, v74, v74
	v_add_f32_e32 v147, v147, v148
	v_add_f32_e32 v243, v146, v147
	s_waitcnt vmcnt(15)
	v_lshlrev_b32_e32 v146, 16, v182
	v_and_b32_e32 v147, 0xffff0000, v182
	v_lshlrev_b32_e32 v148, 16, v183
	v_and_b32_e32 v149, 0xffff0000, v183
	v_lshlrev_b32_e32 v150, 16, v184
	v_and_b32_e32 v151, 0xffff0000, v184
	v_lshlrev_b32_e32 v152, 16, v185
	v_and_b32_e32 v153, 0xffff0000, v185
	v_pk_add_f32 v[70:71], v[70:71], v[148:149]
	v_pk_add_f32 v[68:69], v[68:69], v[146:147]
	v_pk_add_f32 v[66:67], v[66:67], v[152:153]
	v_pk_add_f32 v[64:65], v[64:65], v[150:151]
	v_cvt_pk_bf16_f32 v248, v68, v69
	v_cvt_pk_bf16_f32 v249, v70, v71
	v_cvt_pk_bf16_f32 v250, v64, v65
	v_cvt_pk_bf16_f32 v251, v66, v67
	global_store_dwordx4 v[230:231], v[248:251], off offset:256
	v_mul_f32_e32 v146, v69, v69
	v_mul_f32_e32 v147, v71, v71
	v_fmac_f32_e32 v146, v68, v68
	v_fmac_f32_e32 v147, v70, v70
	v_add_f32_e32 v146, v146, v147
	v_mul_f32_e32 v147, v65, v65
	v_mul_f32_e32 v148, v67, v67
	v_fmac_f32_e32 v147, v64, v64
	v_fmac_f32_e32 v148, v66, v66
	v_add_f32_e32 v147, v147, v148
	v_add_f32_e32 v146, v146, v147
	v_add_f32_e32 v243, v243, v146
	s_waitcnt vmcnt(15)
	v_lshlrev_b32_e32 v146, 16, v186
	v_and_b32_e32 v147, 0xffff0000, v186
	v_lshlrev_b32_e32 v148, 16, v187
	v_and_b32_e32 v149, 0xffff0000, v187
	v_lshlrev_b32_e32 v150, 16, v188
	v_and_b32_e32 v151, 0xffff0000, v188
	v_lshlrev_b32_e32 v152, 16, v189
	v_and_b32_e32 v153, 0xffff0000, v189
	v_pk_add_f32 v[62:63], v[62:63], v[148:149]
	v_pk_add_f32 v[60:61], v[60:61], v[146:147]
	v_pk_add_f32 v[58:59], v[58:59], v[152:153]
	v_pk_add_f32 v[56:57], v[56:57], v[150:151]
	v_cvt_pk_bf16_f32 v136, v60, v61
	v_cvt_pk_bf16_f32 v137, v62, v63
	v_cvt_pk_bf16_f32 v138, v56, v57
	v_cvt_pk_bf16_f32 v139, v58, v59
	global_store_dwordx4 v[232:233], v[136:139], off
	v_mul_f32_e32 v146, v61, v61
	v_mul_f32_e32 v147, v63, v63
	v_fmac_f32_e32 v146, v60, v60
	v_fmac_f32_e32 v147, v62, v62
	v_add_f32_e32 v146, v146, v147
	v_mul_f32_e32 v147, v57, v57
	v_mul_f32_e32 v148, v59, v59
	v_fmac_f32_e32 v147, v56, v56
	v_fmac_f32_e32 v148, v58, v58
	v_add_f32_e32 v147, v147, v148
	v_add_f32_e32 v244, v146, v147
	s_waitcnt vmcnt(15)
	v_lshlrev_b32_e32 v146, 16, v190
	v_and_b32_e32 v147, 0xffff0000, v190
	v_lshlrev_b32_e32 v148, 16, v191
	v_and_b32_e32 v149, 0xffff0000, v191
	v_lshlrev_b32_e32 v150, 16, v192
	v_and_b32_e32 v151, 0xffff0000, v192
	v_lshlrev_b32_e32 v152, 16, v193
	v_and_b32_e32 v153, 0xffff0000, v193
	v_pk_add_f32 v[54:55], v[54:55], v[148:149]
	v_pk_add_f32 v[52:53], v[52:53], v[146:147]
	v_pk_add_f32 v[50:51], v[50:51], v[152:153]
	v_pk_add_f32 v[48:49], v[48:49], v[150:151]
	v_cvt_pk_bf16_f32 v248, v52, v53
	v_cvt_pk_bf16_f32 v249, v54, v55
	v_cvt_pk_bf16_f32 v250, v48, v49
	v_cvt_pk_bf16_f32 v251, v50, v51
	global_store_dwordx4 v[232:233], v[248:251], off offset:256
	v_mul_f32_e32 v146, v53, v53
	v_mul_f32_e32 v147, v55, v55
	v_fmac_f32_e32 v146, v52, v52
	v_fmac_f32_e32 v147, v54, v54
	v_add_f32_e32 v146, v146, v147
	v_mul_f32_e32 v147, v49, v49
	v_mul_f32_e32 v148, v51, v51
	v_fmac_f32_e32 v147, v48, v48
	v_fmac_f32_e32 v148, v50, v50
	v_add_f32_e32 v147, v147, v148
	v_add_f32_e32 v146, v146, v147
	v_add_f32_e32 v244, v244, v146
	s_waitcnt vmcnt(15)
	v_lshlrev_b32_e32 v146, 16, v194
	v_and_b32_e32 v147, 0xffff0000, v194
	v_lshlrev_b32_e32 v148, 16, v195
	v_and_b32_e32 v149, 0xffff0000, v195
	v_lshlrev_b32_e32 v150, 16, v196
	v_and_b32_e32 v151, 0xffff0000, v196
	v_lshlrev_b32_e32 v152, 16, v197
	v_and_b32_e32 v153, 0xffff0000, v197
	v_pk_add_f32 v[46:47], v[46:47], v[148:149]
	v_pk_add_f32 v[44:45], v[44:45], v[146:147]
	v_pk_add_f32 v[42:43], v[42:43], v[152:153]
	v_pk_add_f32 v[40:41], v[40:41], v[150:151]
	v_cvt_pk_bf16_f32 v136, v44, v45
	v_cvt_pk_bf16_f32 v137, v46, v47
	v_cvt_pk_bf16_f32 v138, v40, v41
	v_cvt_pk_bf16_f32 v139, v42, v43
	global_store_dwordx4 v[234:235], v[136:139], off
	v_mul_f32_e32 v146, v45, v45
	v_mul_f32_e32 v147, v47, v47
	v_fmac_f32_e32 v146, v44, v44
	v_fmac_f32_e32 v147, v46, v46
	v_add_f32_e32 v146, v146, v147
	v_mul_f32_e32 v147, v41, v41
	v_mul_f32_e32 v148, v43, v43
	v_fmac_f32_e32 v147, v40, v40
	v_fmac_f32_e32 v148, v42, v42
	v_add_f32_e32 v147, v147, v148
	v_add_f32_e32 v245, v146, v147
	s_waitcnt vmcnt(15)
	v_lshlrev_b32_e32 v146, 16, v198
	v_and_b32_e32 v147, 0xffff0000, v198
	v_lshlrev_b32_e32 v148, 16, v199
	v_and_b32_e32 v149, 0xffff0000, v199
	v_lshlrev_b32_e32 v150, 16, v200
	v_and_b32_e32 v151, 0xffff0000, v200
	v_lshlrev_b32_e32 v152, 16, v201
	v_and_b32_e32 v153, 0xffff0000, v201
	v_pk_add_f32 v[38:39], v[38:39], v[148:149]
	v_pk_add_f32 v[36:37], v[36:37], v[146:147]
	v_pk_add_f32 v[34:35], v[34:35], v[152:153]
	v_pk_add_f32 v[32:33], v[32:33], v[150:151]
	v_cvt_pk_bf16_f32 v248, v36, v37
	v_cvt_pk_bf16_f32 v249, v38, v39
	v_cvt_pk_bf16_f32 v250, v32, v33
	v_cvt_pk_bf16_f32 v251, v34, v35
	global_store_dwordx4 v[234:235], v[248:251], off offset:256
	v_mul_f32_e32 v146, v37, v37
	v_mul_f32_e32 v147, v39, v39
	v_fmac_f32_e32 v146, v36, v36
	v_fmac_f32_e32 v147, v38, v38
	v_add_f32_e32 v146, v146, v147
	v_mul_f32_e32 v147, v33, v33
	v_mul_f32_e32 v148, v35, v35
	v_fmac_f32_e32 v147, v32, v32
	v_fmac_f32_e32 v148, v34, v34
	v_add_f32_e32 v147, v147, v148
	v_add_f32_e32 v146, v146, v147
	v_add_f32_e32 v245, v245, v146
	s_waitcnt vmcnt(15)
	v_lshlrev_b32_e32 v146, 16, v202
	v_and_b32_e32 v147, 0xffff0000, v202
	v_lshlrev_b32_e32 v148, 16, v203
	v_and_b32_e32 v149, 0xffff0000, v203
	v_lshlrev_b32_e32 v150, 16, v204
	v_and_b32_e32 v151, 0xffff0000, v204
	v_lshlrev_b32_e32 v152, 16, v205
	v_and_b32_e32 v153, 0xffff0000, v205
	v_pk_add_f32 v[30:31], v[30:31], v[148:149]
	v_pk_add_f32 v[28:29], v[28:29], v[146:147]
	v_pk_add_f32 v[26:27], v[26:27], v[152:153]
	v_pk_add_f32 v[24:25], v[24:25], v[150:151]
	v_cvt_pk_bf16_f32 v136, v28, v29
	v_cvt_pk_bf16_f32 v137, v30, v31
	v_cvt_pk_bf16_f32 v138, v24, v25
	v_cvt_pk_bf16_f32 v139, v26, v27
	global_store_dwordx4 v[236:237], v[136:139], off
	v_mul_f32_e32 v146, v29, v29
	v_mul_f32_e32 v147, v31, v31
	v_fmac_f32_e32 v146, v28, v28
	v_fmac_f32_e32 v147, v30, v30
	v_add_f32_e32 v146, v146, v147
	v_mul_f32_e32 v147, v25, v25
	v_mul_f32_e32 v148, v27, v27
	v_fmac_f32_e32 v147, v24, v24
	v_fmac_f32_e32 v148, v26, v26
	v_add_f32_e32 v147, v147, v148
	v_add_f32_e32 v246, v146, v147
	s_waitcnt vmcnt(15)
	v_lshlrev_b32_e32 v146, 16, v206
	v_and_b32_e32 v147, 0xffff0000, v206
	v_lshlrev_b32_e32 v148, 16, v207
	v_and_b32_e32 v149, 0xffff0000, v207
	v_lshlrev_b32_e32 v150, 16, v208
	v_and_b32_e32 v151, 0xffff0000, v208
	v_lshlrev_b32_e32 v152, 16, v209
	v_and_b32_e32 v153, 0xffff0000, v209
	v_pk_add_f32 v[22:23], v[22:23], v[148:149]
	v_pk_add_f32 v[20:21], v[20:21], v[146:147]
	v_pk_add_f32 v[18:19], v[18:19], v[152:153]
	v_pk_add_f32 v[16:17], v[16:17], v[150:151]
	v_cvt_pk_bf16_f32 v248, v20, v21
	v_cvt_pk_bf16_f32 v249, v22, v23
	v_cvt_pk_bf16_f32 v250, v16, v17
	v_cvt_pk_bf16_f32 v251, v18, v19
	global_store_dwordx4 v[236:237], v[248:251], off offset:256
	v_mul_f32_e32 v146, v21, v21
	v_mul_f32_e32 v147, v23, v23
	v_fmac_f32_e32 v146, v20, v20
	v_fmac_f32_e32 v147, v22, v22
	v_add_f32_e32 v146, v146, v147
	v_mul_f32_e32 v147, v17, v17
	v_mul_f32_e32 v148, v19, v19
	v_fmac_f32_e32 v147, v16, v16
	v_fmac_f32_e32 v148, v18, v18
	v_add_f32_e32 v147, v147, v148
	v_add_f32_e32 v146, v146, v147
	v_add_f32_e32 v246, v246, v146
	s_waitcnt vmcnt(15)
	v_lshlrev_b32_e32 v146, 16, v210
	v_and_b32_e32 v147, 0xffff0000, v210
	v_lshlrev_b32_e32 v148, 16, v211
	v_and_b32_e32 v149, 0xffff0000, v211
	v_lshlrev_b32_e32 v150, 16, v212
	v_and_b32_e32 v151, 0xffff0000, v212
	v_lshlrev_b32_e32 v152, 16, v213
	v_and_b32_e32 v153, 0xffff0000, v213
	v_pk_add_f32 v[14:15], v[14:15], v[148:149]
	v_pk_add_f32 v[12:13], v[12:13], v[146:147]
	v_pk_add_f32 v[10:11], v[10:11], v[152:153]
	v_pk_add_f32 v[8:9], v[8:9], v[150:151]
	v_cvt_pk_bf16_f32 v136, v12, v13
	v_cvt_pk_bf16_f32 v137, v14, v15
	v_cvt_pk_bf16_f32 v138, v8, v9
	v_cvt_pk_bf16_f32 v139, v10, v11
	global_store_dwordx4 v[238:239], v[136:139], off
	v_mul_f32_e32 v146, v13, v13
	v_mul_f32_e32 v147, v15, v15
	v_fmac_f32_e32 v146, v12, v12
	v_fmac_f32_e32 v147, v14, v14
	v_add_f32_e32 v146, v146, v147
	v_mul_f32_e32 v147, v9, v9
	v_mul_f32_e32 v148, v11, v11
	v_fmac_f32_e32 v147, v8, v8
	v_fmac_f32_e32 v148, v10, v10
	v_add_f32_e32 v147, v147, v148
	v_add_f32_e32 v247, v146, v147
	s_waitcnt vmcnt(15)
	v_lshlrev_b32_e32 v146, 16, v220
	v_and_b32_e32 v147, 0xffff0000, v220
	v_lshlrev_b32_e32 v148, 16, v221
	v_and_b32_e32 v149, 0xffff0000, v221
	v_lshlrev_b32_e32 v150, 16, v222
	v_and_b32_e32 v151, 0xffff0000, v222
	v_lshlrev_b32_e32 v152, 16, v223
	v_and_b32_e32 v153, 0xffff0000, v223
	v_pk_add_f32 v[6:7], v[6:7], v[148:149]
	v_pk_add_f32 v[4:5], v[4:5], v[146:147]
	v_pk_add_f32 v[2:3], v[2:3], v[152:153]
	v_pk_add_f32 v[0:1], v[0:1], v[150:151]
	v_cvt_pk_bf16_f32 v248, v4, v5
	v_cvt_pk_bf16_f32 v249, v6, v7
	v_cvt_pk_bf16_f32 v250, v0, v1
	v_cvt_pk_bf16_f32 v251, v2, v3
	global_store_dwordx4 v[238:239], v[248:251], off offset:256
	v_mul_f32_e32 v146, v5, v5
	v_mul_f32_e32 v147, v7, v7
	v_fmac_f32_e32 v146, v4, v4
	v_fmac_f32_e32 v147, v6, v6
	v_add_f32_e32 v146, v146, v147
	v_mul_f32_e32 v147, v1, v1
	v_mul_f32_e32 v148, v3, v3
	v_fmac_f32_e32 v147, v0, v0
	v_fmac_f32_e32 v148, v2, v2
	v_add_f32_e32 v147, v147, v148
	v_add_f32_e32 v146, v146, v147
	v_add_f32_e32 v247, v247, v146
	ds_bpermute_b32 v154, v145, v240
	ds_bpermute_b32 v155, v145, v241
	ds_bpermute_b32 v156, v145, v242
	ds_bpermute_b32 v157, v145, v243
	ds_bpermute_b32 v158, v145, v244
	ds_bpermute_b32 v159, v145, v245
	ds_bpermute_b32 v160, v145, v246
	ds_bpermute_b32 v161, v145, v247
	s_waitcnt lgkmcnt(7)
	v_add_f32_e32 v240, v240, v154
	ds_bpermute_b32 v154, v144, v240
	s_waitcnt lgkmcnt(7)
	v_add_f32_e32 v241, v241, v155
	ds_bpermute_b32 v155, v144, v241
	s_waitcnt lgkmcnt(7)
	v_add_f32_e32 v242, v242, v156
	ds_bpermute_b32 v156, v144, v242
	s_waitcnt lgkmcnt(7)
	v_add_f32_e32 v243, v243, v157
	ds_bpermute_b32 v157, v144, v243
	s_waitcnt lgkmcnt(7)
	v_add_f32_e32 v244, v244, v158
	ds_bpermute_b32 v158, v144, v244
	s_waitcnt lgkmcnt(7)
	v_add_f32_e32 v245, v245, v159
	ds_bpermute_b32 v159, v144, v245
	s_waitcnt lgkmcnt(7)
	v_add_f32_e32 v246, v246, v160
	ds_bpermute_b32 v160, v144, v246
	s_waitcnt lgkmcnt(7)
	v_add_f32_e32 v247, v247, v161
	ds_bpermute_b32 v161, v144, v247
	s_and_saveexec_b64 s[38:39], vcc
	s_waitcnt lgkmcnt(7)
	v_add_f32_e32 v240, v240, v154
	global_store_dword v[140:141], v240, off
	s_waitcnt lgkmcnt(6)
	v_add_f32_e32 v241, v241, v155
	global_store_dword v[140:141], v241, off offset:1024
	s_waitcnt lgkmcnt(5)
	v_add_f32_e32 v242, v242, v156
	global_store_dword v[140:141], v242, off offset:2048
	s_waitcnt lgkmcnt(4)
	v_add_f32_e32 v243, v243, v157
	global_store_dword v[140:141], v243, off offset:3072
	s_waitcnt lgkmcnt(3)
	v_add_f32_e32 v244, v244, v158
	global_store_dword v[252:253], v244, off
	s_waitcnt lgkmcnt(2)
	v_add_f32_e32 v245, v245, v159
	global_store_dword v[252:253], v245, off offset:1024
	s_waitcnt lgkmcnt(1)
	v_add_f32_e32 v246, v246, v160
	global_store_dword v[252:253], v246, off offset:2048
	s_waitcnt lgkmcnt(0)
	v_add_f32_e32 v247, v247, v161
	global_store_dword v[252:253], v247, off offset:3072
	s_or_b64 exec, exec, s[38:39]
	s_andn2_b64 vcc, exec, s[6:7]
	s_mov_b64 s[6:7], -1
	s_cbranch_vccnz .LBB0_114
	s_andn2_b64 vcc, exec, s[8:9]
	s_cbranch_vccnz .LBB0_113
	s_barrier
	s_branch .LBB0_113

.LBB0_706:
	v_and_b32_e32 v141, 64, v217
	v_xor_b32_e32 v140, 16, v217
	v_add_u32_e32 v141, 64, v141
	s_lshl_b32 s18, s20, 8
	v_cmp_lt_i32_e32 vcc, v140, v141
	s_add_i32 s18, s18, s72
	v_mbcnt_lo_u32_b32 v136, -1, 0
	v_mbcnt_hi_u32_b32 v136, -1, v136
	s_nop 0
	v_cndmask_b32_e32 v140, v217, v140, vcc
	v_and_or_b32 v138, v136, 15, s18
	s_lshl_b32 s18, s16, 8
	v_lshlrev_b32_e32 v145, 2, v140
	v_xor_b32_e32 v140, 32, v217
	v_bfe_u32 v139, v136, 4, 2
	s_or_b32 s18, s18, s73
	v_cmp_lt_i32_e32 vcc, v140, v141
	v_lshl_or_b32 v136, v139, 3, s18
	v_ashrrev_i32_e32 v137, 31, v136
	s_nop 0
	v_cndmask_b32_e32 v140, v217, v140, vcc
	v_cmp_eq_u32_e32 vcc, 0, v139
	v_ashrrev_i32_e32 v139, 31, v138
	v_lshlrev_b32_e32 v144, 2, v140
	v_lshlrev_b64 v[140:141], 11, v[138:139]
	v_lshl_add_u64 v[140:141], s[22:23], 0, v[140:141]
	v_lshl_add_u64 v[224:225], v[136:137], 1, v[140:141]
	s_lshl_b32 s60, s16, 2
	s_ashr_i32 s61, s60, 31
	s_mov_b32 s101, 0
	v_lshlrev_b64 v[140:141], 6, v[138:139]
	v_lshl_add_u64 v[140:141], s[28:29], 0, v[140:141]
	v_lshl_add_u64 v[140:141], s[60:61], 2, v[140:141]
	s_lshl_b32 s20, s71, 2
	v_lshl_add_u64 v[140:141], v[140:141], 0, s[20:21]
	s_mov_b32 s100, 0x2000
	v_lshl_add_u64 v[252:253], s[100:101], 0, v[140:141]
	global_load_dwordx4 v[154:157], v[224:225], off
	global_load_dwordx4 v[158:161], v[224:225], off offset:256
	s_mov_b32 s100, 0x8000
	v_lshl_add_u64 v[226:227], s[100:101], 0, v[224:225]
	global_load_dwordx4 v[162:165], v[226:227], off
	global_load_dwordx4 v[166:169], v[226:227], off offset:256
	s_mov_b32 s100, 0x8000
	v_lshl_add_u64 v[228:229], s[100:101], 0, v[226:227]
	global_load_dwordx4 v[170:173], v[228:229], off
	global_load_dwordx4 v[174:177], v[228:229], off offset:256
	s_mov_b32 s100, 0x8000
	v_lshl_add_u64 v[230:231], s[100:101], 0, v[228:229]
	global_load_dwordx4 v[178:181], v[230:231], off
	global_load_dwordx4 v[182:185], v[230:231], off offset:256
	s_mov_b32 s100, 0x28000
	v_lshl_add_u64 v[232:233], s[100:101], 0, v[230:231]
	global_load_dwordx4 v[186:189], v[232:233], off
	global_load_dwordx4 v[190:193], v[232:233], off offset:256
	s_mov_b32 s100, 0x8000
	v_lshl_add_u64 v[234:235], s[100:101], 0, v[232:233]
	global_load_dwordx4 v[194:197], v[234:235], off
	global_load_dwordx4 v[198:201], v[234:235], off offset:256
	s_mov_b32 s100, 0x8000
	v_lshl_add_u64 v[236:237], s[100:101], 0, v[234:235]
	global_load_dwordx4 v[202:205], v[236:237], off
	global_load_dwordx4 v[206:209], v[236:237], off offset:256
	s_mov_b32 s100, 0x8000
	v_lshl_add_u64 v[238:239], s[100:101], 0, v[236:237]
	global_load_dwordx4 v[210:213], v[238:239], off
	global_load_dwordx4 v[220:223], v[238:239], off offset:256
	s_waitcnt vmcnt(15)
	v_lshlrev_b32_e32 v146, 16, v154
	v_and_b32_e32 v147, 0xffff0000, v154
	v_lshlrev_b32_e32 v148, 16, v155
	v_and_b32_e32 v149, 0xffff0000, v155
	v_lshlrev_b32_e32 v150, 16, v156
	v_and_b32_e32 v151, 0xffff0000, v156
	v_lshlrev_b32_e32 v152, 16, v157
	v_and_b32_e32 v153, 0xffff0000, v157
	v_pk_fma_f32 v[128:129], v[128:129], 0.5, v[148:149] op_sel_hi:[1,0,1]
	v_pk_fma_f32 v[126:127], v[126:127], 0.5, v[146:147] op_sel_hi:[1,0,1]
	v_pk_fma_f32 v[124:125], v[124:125], 0.5, v[152:153] op_sel_hi:[1,0,1]
	v_pk_fma_f32 v[122:123], v[122:123], 0.5, v[150:151] op_sel_hi:[1,0,1]
	v_cvt_pk_bf16_f32 v136, v126, v127
	v_cvt_pk_bf16_f32 v137, v128, v129
	v_cvt_pk_bf16_f32 v138, v122, v123
	v_cvt_pk_bf16_f32 v139, v124, v125
	global_store_dwordx4 v[224:225], v[136:139], off
	v_mul_f32_e32 v146, v127, v127
	v_mul_f32_e32 v147, v129, v129
	v_fmac_f32_e32 v146, v126, v126
	v_fmac_f32_e32 v147, v128, v128
	v_add_f32_e32 v146, v146, v147
	v_mul_f32_e32 v147, v123, v123
	v_mul_f32_e32 v148, v125, v125
	v_fmac_f32_e32 v147, v122, v122
	v_fmac_f32_e32 v148, v124, v124
	v_add_f32_e32 v147, v147, v148
	v_add_f32_e32 v240, v146, v147
	s_waitcnt vmcnt(15)
	v_lshlrev_b32_e32 v146, 16, v158
	v_and_b32_e32 v147, 0xffff0000, v158
	v_lshlrev_b32_e32 v148, 16, v159
	v_and_b32_e32 v149, 0xffff0000, v159
	v_lshlrev_b32_e32 v150, 16, v160
	v_and_b32_e32 v151, 0xffff0000, v160
	v_lshlrev_b32_e32 v152, 16, v161
	v_and_b32_e32 v153, 0xffff0000, v161
	v_pk_fma_f32 v[120:121], v[120:121], 0.5, v[148:149] op_sel_hi:[1,0,1]
	v_pk_fma_f32 v[118:119], v[118:119], 0.5, v[146:147] op_sel_hi:[1,0,1]
	v_pk_fma_f32 v[116:117], v[116:117], 0.5, v[152:153] op_sel_hi:[1,0,1]
	v_pk_fma_f32 v[114:115], v[114:115], 0.5, v[150:151] op_sel_hi:[1,0,1]
	v_cvt_pk_bf16_f32 v248, v118, v119
	v_cvt_pk_bf16_f32 v249, v120, v121
	v_cvt_pk_bf16_f32 v250, v114, v115
	v_cvt_pk_bf16_f32 v251, v116, v117
	global_store_dwordx4 v[224:225], v[248:251], off offset:256
	v_mul_f32_e32 v146, v119, v119
	v_mul_f32_e32 v147, v121, v121
	v_fmac_f32_e32 v146, v118, v118
	v_fmac_f32_e32 v147, v120, v120
	v_add_f32_e32 v146, v146, v147
	v_mul_f32_e32 v147, v115, v115
	v_mul_f32_e32 v148, v117, v117
	v_fmac_f32_e32 v147, v114, v114
	v_fmac_f32_e32 v148, v116, v116
	v_add_f32_e32 v147, v147, v148
	v_add_f32_e32 v146, v146, v147
	v_add_f32_e32 v240, v240, v146
	s_waitcnt vmcnt(15)
	v_lshlrev_b32_e32 v146, 16, v162
	v_and_b32_e32 v147, 0xffff0000, v162
	v_lshlrev_b32_e32 v148, 16, v163
	v_and_b32_e32 v149, 0xffff0000, v163
	v_lshlrev_b32_e32 v150, 16, v164
	v_and_b32_e32 v151, 0xffff0000, v164
	v_lshlrev_b32_e32 v152, 16, v165
	v_and_b32_e32 v153, 0xffff0000, v165
	v_pk_fma_f32 v[112:113], v[112:113], 0.5, v[148:149] op_sel_hi:[1,0,1]
	v_pk_fma_f32 v[110:111], v[110:111], 0.5, v[146:147] op_sel_hi:[1,0,1]
	v_pk_fma_f32 v[108:109], v[108:109], 0.5, v[152:153] op_sel_hi:[1,0,1]
	v_pk_fma_f32 v[106:107], v[106:107], 0.5, v[150:151] op_sel_hi:[1,0,1]
	v_cvt_pk_bf16_f32 v136, v110, v111
	v_cvt_pk_bf16_f32 v137, v112, v113
	v_cvt_pk_bf16_f32 v138, v106, v107
	v_cvt_pk_bf16_f32 v139, v108, v109
	global_store_dwordx4 v[226:227], v[136:139], off
	v_mul_f32_e32 v146, v111, v111
	v_mul_f32_e32 v147, v113, v113
	v_fmac_f32_e32 v146, v110, v110
	v_fmac_f32_e32 v147, v112, v112
	v_add_f32_e32 v146, v146, v147
	v_mul_f32_e32 v147, v107, v107
	v_mul_f32_e32 v148, v109, v109
	v_fmac_f32_e32 v147, v106, v106
	v_fmac_f32_e32 v148, v108, v108
	v_add_f32_e32 v147, v147, v148
	v_add_f32_e32 v241, v146, v147
	s_waitcnt vmcnt(15)
	v_lshlrev_b32_e32 v146, 16, v166
	v_and_b32_e32 v147, 0xffff0000, v166
	v_lshlrev_b32_e32 v148, 16, v167
	v_and_b32_e32 v149, 0xffff0000, v167
	v_lshlrev_b32_e32 v150, 16, v168
	v_and_b32_e32 v151, 0xffff0000, v168
	v_lshlrev_b32_e32 v152, 16, v169
	v_and_b32_e32 v153, 0xffff0000, v169
	v_pk_fma_f32 v[104:105], v[104:105], 0.5, v[148:149] op_sel_hi:[1,0,1]
	v_pk_fma_f32 v[102:103], v[102:103], 0.5, v[146:147] op_sel_hi:[1,0,1]
	v_pk_fma_f32 v[100:101], v[100:101], 0.5, v[152:153] op_sel_hi:[1,0,1]
	v_pk_fma_f32 v[98:99], v[98:99], 0.5, v[150:151] op_sel_hi:[1,0,1]
	v_cvt_pk_bf16_f32 v248, v102, v103
	v_cvt_pk_bf16_f32 v249, v104, v105
	v_cvt_pk_bf16_f32 v250, v98, v99
	v_cvt_pk_bf16_f32 v251, v100, v101
	global_store_dwordx4 v[226:227], v[248:251], off offset:256
	v_mul_f32_e32 v146, v103, v103
	v_mul_f32_e32 v147, v105, v105
	v_fmac_f32_e32 v146, v102, v102
	v_fmac_f32_e32 v147, v104, v104
	v_add_f32_e32 v146, v146, v147
	v_mul_f32_e32 v147, v99, v99
	v_mul_f32_e32 v148, v101, v101
	v_fmac_f32_e32 v147, v98, v98
	v_fmac_f32_e32 v148, v100, v100
	v_add_f32_e32 v147, v147, v148
	v_add_f32_e32 v146, v146, v147
	v_add_f32_e32 v241, v241, v146
	s_waitcnt vmcnt(15)
	v_lshlrev_b32_e32 v146, 16, v170
	v_and_b32_e32 v147, 0xffff0000, v170
	v_lshlrev_b32_e32 v148, 16, v171
	v_and_b32_e32 v149, 0xffff0000, v171
	v_lshlrev_b32_e32 v150, 16, v172
	v_and_b32_e32 v151, 0xffff0000, v172
	v_lshlrev_b32_e32 v152, 16, v173
	v_and_b32_e32 v153, 0xffff0000, v173
	v_pk_fma_f32 v[94:95], v[94:95], 0.5, v[148:149] op_sel_hi:[1,0,1]
	v_pk_fma_f32 v[92:93], v[92:93], 0.5, v[146:147] op_sel_hi:[1,0,1]
	v_pk_fma_f32 v[90:91], v[90:91], 0.5, v[152:153] op_sel_hi:[1,0,1]
	v_pk_fma_f32 v[88:89], v[88:89], 0.5, v[150:151] op_sel_hi:[1,0,1]
	v_cvt_pk_bf16_f32 v136, v92, v93
	v_cvt_pk_bf16_f32 v137, v94, v95
	v_cvt_pk_bf16_f32 v138, v88, v89
	v_cvt_pk_bf16_f32 v139, v90, v91
	global_store_dwordx4 v[228:229], v[136:139], off
	v_mul_f32_e32 v146, v93, v93
	v_mul_f32_e32 v147, v95, v95
	v_fmac_f32_e32 v146, v92, v92
	v_fmac_f32_e32 v147, v94, v94
	v_add_f32_e32 v146, v146, v147
	v_mul_f32_e32 v147, v89, v89
	v_mul_f32_e32 v148, v91, v91
	v_fmac_f32_e32 v147, v88, v88
	v_fmac_f32_e32 v148, v90, v90
	v_add_f32_e32 v147, v147, v148
	v_add_f32_e32 v242, v146, v147
	s_waitcnt vmcnt(15)
	v_lshlrev_b32_e32 v146, 16, v174
	v_and_b32_e32 v147, 0xffff0000, v174
	v_lshlrev_b32_e32 v148, 16, v175
	v_and_b32_e32 v149, 0xffff0000, v175
	v_lshlrev_b32_e32 v150, 16, v176
	v_and_b32_e32 v151, 0xffff0000, v176
	v_lshlrev_b32_e32 v152, 16, v177
	v_and_b32_e32 v153, 0xffff0000, v177
	v_pk_fma_f32 v[86:87], v[86:87], 0.5, v[148:149] op_sel_hi:[1,0,1]
	v_pk_fma_f32 v[84:85], v[84:85], 0.5, v[146:147] op_sel_hi:[1,0,1]
	v_pk_fma_f32 v[82:83], v[82:83], 0.5, v[152:153] op_sel_hi:[1,0,1]
	v_pk_fma_f32 v[80:81], v[80:81], 0.5, v[150:151] op_sel_hi:[1,0,1]
	v_cvt_pk_bf16_f32 v248, v84, v85
	v_cvt_pk_bf16_f32 v249, v86, v87
	v_cvt_pk_bf16_f32 v250, v80, v81
	v_cvt_pk_bf16_f32 v251, v82, v83
	global_store_dwordx4 v[228:229], v[248:251], off offset:256
	v_mul_f32_e32 v146, v85, v85
	v_mul_f32_e32 v147, v87, v87
	v_fmac_f32_e32 v146, v84, v84
	v_fmac_f32_e32 v147, v86, v86
	v_add_f32_e32 v146, v146, v147
	v_mul_f32_e32 v147, v81, v81
	v_mul_f32_e32 v148, v83, v83
	v_fmac_f32_e32 v147, v80, v80
	v_fmac_f32_e32 v148, v82, v82
	v_add_f32_e32 v147, v147, v148
	v_add_f32_e32 v146, v146, v147
	v_add_f32_e32 v242, v242, v146
	s_waitcnt vmcnt(15)
	v_lshlrev_b32_e32 v146, 16, v178
	v_and_b32_e32 v147, 0xffff0000, v178
	v_lshlrev_b32_e32 v148, 16, v179
	v_and_b32_e32 v149, 0xffff0000, v179
	v_lshlrev_b32_e32 v150, 16, v180
	v_and_b32_e32 v151, 0xffff0000, v180
	v_lshlrev_b32_e32 v152, 16, v181
	v_and_b32_e32 v153, 0xffff0000, v181
	v_pk_fma_f32 v[78:79], v[78:79], 0.5, v[148:149] op_sel_hi:[1,0,1]
	v_pk_fma_f32 v[76:77], v[76:77], 0.5, v[146:147] op_sel_hi:[1,0,1]
	v_pk_fma_f32 v[74:75], v[74:75], 0.5, v[152:153] op_sel_hi:[1,0,1]
	v_pk_fma_f32 v[72:73], v[72:73], 0.5, v[150:151] op_sel_hi:[1,0,1]
	v_cvt_pk_bf16_f32 v136, v76, v77
	v_cvt_pk_bf16_f32 v137, v78, v79
	v_cvt_pk_bf16_f32 v138, v72, v73
	v_cvt_pk_bf16_f32 v139, v74, v75
	global_store_dwordx4 v[230:231], v[136:139], off
	v_mul_f32_e32 v146, v77, v77
	v_mul_f32_e32 v147, v79, v79
	v_fmac_f32_e32 v146, v76, v76
	v_fmac_f32_e32 v147, v78, v78
	v_add_f32_e32 v146, v146, v147
	v_mul_f32_e32 v147, v73, v73
	v_mul_f32_e32 v148, v75, v75
	v_fmac_f32_e32 v147, v72, v72
	v_fmac_f32_e32 v148, v74, v74
	v_add_f32_e32 v147, v147, v148
	v_add_f32_e32 v243, v146, v147
	s_waitcnt vmcnt(15)
	v_lshlrev_b32_e32 v146, 16, v182
	v_and_b32_e32 v147, 0xffff0000, v182
	v_lshlrev_b32_e32 v148, 16, v183
	v_and_b32_e32 v149, 0xffff0000, v183
	v_lshlrev_b32_e32 v150, 16, v184
	v_and_b32_e32 v151, 0xffff0000, v184
	v_lshlrev_b32_e32 v152, 16, v185
	v_and_b32_e32 v153, 0xffff0000, v185
	v_pk_fma_f32 v[70:71], v[70:71], 0.5, v[148:149] op_sel_hi:[1,0,1]
	v_pk_fma_f32 v[68:69], v[68:69], 0.5, v[146:147] op_sel_hi:[1,0,1]
	v_pk_fma_f32 v[66:67], v[66:67], 0.5, v[152:153] op_sel_hi:[1,0,1]
	v_pk_fma_f32 v[64:65], v[64:65], 0.5, v[150:151] op_sel_hi:[1,0,1]
	v_cvt_pk_bf16_f32 v248, v68, v69
	v_cvt_pk_bf16_f32 v249, v70, v71
	v_cvt_pk_bf16_f32 v250, v64, v65
	v_cvt_pk_bf16_f32 v251, v66, v67
	global_store_dwordx4 v[230:231], v[248:251], off offset:256
	v_mul_f32_e32 v146, v69, v69
	v_mul_f32_e32 v147, v71, v71
	v_fmac_f32_e32 v146, v68, v68
	v_fmac_f32_e32 v147, v70, v70
	v_add_f32_e32 v146, v146, v147
	v_mul_f32_e32 v147, v65, v65
	v_mul_f32_e32 v148, v67, v67
	v_fmac_f32_e32 v147, v64, v64
	v_fmac_f32_e32 v148, v66, v66
	v_add_f32_e32 v147, v147, v148
	v_add_f32_e32 v146, v146, v147
	v_add_f32_e32 v243, v243, v146
	s_waitcnt vmcnt(15)
	v_lshlrev_b32_e32 v146, 16, v186
	v_and_b32_e32 v147, 0xffff0000, v186
	v_lshlrev_b32_e32 v148, 16, v187
	v_and_b32_e32 v149, 0xffff0000, v187
	v_lshlrev_b32_e32 v150, 16, v188
	v_and_b32_e32 v151, 0xffff0000, v188
	v_lshlrev_b32_e32 v152, 16, v189
	v_and_b32_e32 v153, 0xffff0000, v189
	v_pk_fma_f32 v[62:63], v[62:63], 0.5, v[148:149] op_sel_hi:[1,0,1]
	v_pk_fma_f32 v[60:61], v[60:61], 0.5, v[146:147] op_sel_hi:[1,0,1]
	v_pk_fma_f32 v[58:59], v[58:59], 0.5, v[152:153] op_sel_hi:[1,0,1]
	v_pk_fma_f32 v[56:57], v[56:57], 0.5, v[150:151] op_sel_hi:[1,0,1]
	v_cvt_pk_bf16_f32 v136, v60, v61
	v_cvt_pk_bf16_f32 v137, v62, v63
	v_cvt_pk_bf16_f32 v138, v56, v57
	v_cvt_pk_bf16_f32 v139, v58, v59
	global_store_dwordx4 v[232:233], v[136:139], off
	v_mul_f32_e32 v146, v61, v61
	v_mul_f32_e32 v147, v63, v63
	v_fmac_f32_e32 v146, v60, v60
	v_fmac_f32_e32 v147, v62, v62
	v_add_f32_e32 v146, v146, v147
	v_mul_f32_e32 v147, v57, v57
	v_mul_f32_e32 v148, v59, v59
	v_fmac_f32_e32 v147, v56, v56
	v_fmac_f32_e32 v148, v58, v58
	v_add_f32_e32 v147, v147, v148
	v_add_f32_e32 v244, v146, v147
	s_waitcnt vmcnt(15)
	v_lshlrev_b32_e32 v146, 16, v190
	v_and_b32_e32 v147, 0xffff0000, v190
	v_lshlrev_b32_e32 v148, 16, v191
	v_and_b32_e32 v149, 0xffff0000, v191
	v_lshlrev_b32_e32 v150, 16, v192
	v_and_b32_e32 v151, 0xffff0000, v192
	v_lshlrev_b32_e32 v152, 16, v193
	v_and_b32_e32 v153, 0xffff0000, v193
	v_pk_fma_f32 v[54:55], v[54:55], 0.5, v[148:149] op_sel_hi:[1,0,1]
	v_pk_fma_f32 v[52:53], v[52:53], 0.5, v[146:147] op_sel_hi:[1,0,1]
	v_pk_fma_f32 v[50:51], v[50:51], 0.5, v[152:153] op_sel_hi:[1,0,1]
	v_pk_fma_f32 v[48:49], v[48:49], 0.5, v[150:151] op_sel_hi:[1,0,1]
	v_cvt_pk_bf16_f32 v248, v52, v53
	v_cvt_pk_bf16_f32 v249, v54, v55
	v_cvt_pk_bf16_f32 v250, v48, v49
	v_cvt_pk_bf16_f32 v251, v50, v51
	global_store_dwordx4 v[232:233], v[248:251], off offset:256
	v_mul_f32_e32 v146, v53, v53
	v_mul_f32_e32 v147, v55, v55
	v_fmac_f32_e32 v146, v52, v52
	v_fmac_f32_e32 v147, v54, v54
	v_add_f32_e32 v146, v146, v147
	v_mul_f32_e32 v147, v49, v49
	v_mul_f32_e32 v148, v51, v51
	v_fmac_f32_e32 v147, v48, v48
	v_fmac_f32_e32 v148, v50, v50
	v_add_f32_e32 v147, v147, v148
	v_add_f32_e32 v146, v146, v147
	v_add_f32_e32 v244, v244, v146
	s_waitcnt vmcnt(15)
	v_lshlrev_b32_e32 v146, 16, v194
	v_and_b32_e32 v147, 0xffff0000, v194
	v_lshlrev_b32_e32 v148, 16, v195
	v_and_b32_e32 v149, 0xffff0000, v195
	v_lshlrev_b32_e32 v150, 16, v196
	v_and_b32_e32 v151, 0xffff0000, v196
	v_lshlrev_b32_e32 v152, 16, v197
	v_and_b32_e32 v153, 0xffff0000, v197
	v_pk_fma_f32 v[46:47], v[46:47], 0.5, v[148:149] op_sel_hi:[1,0,1]
	v_pk_fma_f32 v[44:45], v[44:45], 0.5, v[146:147] op_sel_hi:[1,0,1]
	v_pk_fma_f32 v[42:43], v[42:43], 0.5, v[152:153] op_sel_hi:[1,0,1]
	v_pk_fma_f32 v[40:41], v[40:41], 0.5, v[150:151] op_sel_hi:[1,0,1]
	v_cvt_pk_bf16_f32 v136, v44, v45
	v_cvt_pk_bf16_f32 v137, v46, v47
	v_cvt_pk_bf16_f32 v138, v40, v41
	v_cvt_pk_bf16_f32 v139, v42, v43
	global_store_dwordx4 v[234:235], v[136:139], off
	v_mul_f32_e32 v146, v45, v45
	v_mul_f32_e32 v147, v47, v47
	v_fmac_f32_e32 v146, v44, v44
	v_fmac_f32_e32 v147, v46, v46
	v_add_f32_e32 v146, v146, v147
	v_mul_f32_e32 v147, v41, v41
	v_mul_f32_e32 v148, v43, v43
	v_fmac_f32_e32 v147, v40, v40
	v_fmac_f32_e32 v148, v42, v42
	v_add_f32_e32 v147, v147, v148
	v_add_f32_e32 v245, v146, v147
	s_waitcnt vmcnt(15)
	v_lshlrev_b32_e32 v146, 16, v198
	v_and_b32_e32 v147, 0xffff0000, v198
	v_lshlrev_b32_e32 v148, 16, v199
	v_and_b32_e32 v149, 0xffff0000, v199
	v_lshlrev_b32_e32 v150, 16, v200
	v_and_b32_e32 v151, 0xffff0000, v200
	v_lshlrev_b32_e32 v152, 16, v201
	v_and_b32_e32 v153, 0xffff0000, v201
	v_pk_fma_f32 v[38:39], v[38:39], 0.5, v[148:149] op_sel_hi:[1,0,1]
	v_pk_fma_f32 v[36:37], v[36:37], 0.5, v[146:147] op_sel_hi:[1,0,1]
	v_pk_fma_f32 v[34:35], v[34:35], 0.5, v[152:153] op_sel_hi:[1,0,1]
	v_pk_fma_f32 v[32:33], v[32:33], 0.5, v[150:151] op_sel_hi:[1,0,1]
	v_cvt_pk_bf16_f32 v248, v36, v37
	v_cvt_pk_bf16_f32 v249, v38, v39
	v_cvt_pk_bf16_f32 v250, v32, v33
	v_cvt_pk_bf16_f32 v251, v34, v35
	global_store_dwordx4 v[234:235], v[248:251], off offset:256
	v_mul_f32_e32 v146, v37, v37
	v_mul_f32_e32 v147, v39, v39
	v_fmac_f32_e32 v146, v36, v36
	v_fmac_f32_e32 v147, v38, v38
	v_add_f32_e32 v146, v146, v147
	v_mul_f32_e32 v147, v33, v33
	v_mul_f32_e32 v148, v35, v35
	v_fmac_f32_e32 v147, v32, v32
	v_fmac_f32_e32 v148, v34, v34
	v_add_f32_e32 v147, v147, v148
	v_add_f32_e32 v146, v146, v147
	v_add_f32_e32 v245, v245, v146
	s_waitcnt vmcnt(15)
	v_lshlrev_b32_e32 v146, 16, v202
	v_and_b32_e32 v147, 0xffff0000, v202
	v_lshlrev_b32_e32 v148, 16, v203
	v_and_b32_e32 v149, 0xffff0000, v203
	v_lshlrev_b32_e32 v150, 16, v204
	v_and_b32_e32 v151, 0xffff0000, v204
	v_lshlrev_b32_e32 v152, 16, v205
	v_and_b32_e32 v153, 0xffff0000, v205
	v_pk_fma_f32 v[30:31], v[30:31], 0.5, v[148:149] op_sel_hi:[1,0,1]
	v_pk_fma_f32 v[28:29], v[28:29], 0.5, v[146:147] op_sel_hi:[1,0,1]
	v_pk_fma_f32 v[26:27], v[26:27], 0.5, v[152:153] op_sel_hi:[1,0,1]
	v_pk_fma_f32 v[24:25], v[24:25], 0.5, v[150:151] op_sel_hi:[1,0,1]
	v_cvt_pk_bf16_f32 v136, v28, v29
	v_cvt_pk_bf16_f32 v137, v30, v31
	v_cvt_pk_bf16_f32 v138, v24, v25
	v_cvt_pk_bf16_f32 v139, v26, v27
	global_store_dwordx4 v[236:237], v[136:139], off
	v_mul_f32_e32 v146, v29, v29
	v_mul_f32_e32 v147, v31, v31
	v_fmac_f32_e32 v146, v28, v28
	v_fmac_f32_e32 v147, v30, v30
	v_add_f32_e32 v146, v146, v147
	v_mul_f32_e32 v147, v25, v25
	v_mul_f32_e32 v148, v27, v27
	v_fmac_f32_e32 v147, v24, v24
	v_fmac_f32_e32 v148, v26, v26
	v_add_f32_e32 v147, v147, v148
	v_add_f32_e32 v246, v146, v147
	s_waitcnt vmcnt(15)
	v_lshlrev_b32_e32 v146, 16, v206
	v_and_b32_e32 v147, 0xffff0000, v206
	v_lshlrev_b32_e32 v148, 16, v207
	v_and_b32_e32 v149, 0xffff0000, v207
	v_lshlrev_b32_e32 v150, 16, v208
	v_and_b32_e32 v151, 0xffff0000, v208
	v_lshlrev_b32_e32 v152, 16, v209
	v_and_b32_e32 v153, 0xffff0000, v209
	v_pk_fma_f32 v[22:23], v[22:23], 0.5, v[148:149] op_sel_hi:[1,0,1]
	v_pk_fma_f32 v[20:21], v[20:21], 0.5, v[146:147] op_sel_hi:[1,0,1]
	v_pk_fma_f32 v[18:19], v[18:19], 0.5, v[152:153] op_sel_hi:[1,0,1]
	v_pk_fma_f32 v[16:17], v[16:17], 0.5, v[150:151] op_sel_hi:[1,0,1]
	v_cvt_pk_bf16_f32 v248, v20, v21
	v_cvt_pk_bf16_f32 v249, v22, v23
	v_cvt_pk_bf16_f32 v250, v16, v17
	v_cvt_pk_bf16_f32 v251, v18, v19
	global_store_dwordx4 v[236:237], v[248:251], off offset:256
	v_mul_f32_e32 v146, v21, v21
	v_mul_f32_e32 v147, v23, v23
	v_fmac_f32_e32 v146, v20, v20
	v_fmac_f32_e32 v147, v22, v22
	v_add_f32_e32 v146, v146, v147
	v_mul_f32_e32 v147, v17, v17
	v_mul_f32_e32 v148, v19, v19
	v_fmac_f32_e32 v147, v16, v16
	v_fmac_f32_e32 v148, v18, v18
	v_add_f32_e32 v147, v147, v148
	v_add_f32_e32 v146, v146, v147
	v_add_f32_e32 v246, v246, v146
	s_waitcnt vmcnt(15)
	v_lshlrev_b32_e32 v146, 16, v210
	v_and_b32_e32 v147, 0xffff0000, v210
	v_lshlrev_b32_e32 v148, 16, v211
	v_and_b32_e32 v149, 0xffff0000, v211
	v_lshlrev_b32_e32 v150, 16, v212
	v_and_b32_e32 v151, 0xffff0000, v212
	v_lshlrev_b32_e32 v152, 16, v213
	v_and_b32_e32 v153, 0xffff0000, v213
	v_pk_fma_f32 v[14:15], v[14:15], 0.5, v[148:149] op_sel_hi:[1,0,1]
	v_pk_fma_f32 v[12:13], v[12:13], 0.5, v[146:147] op_sel_hi:[1,0,1]
	v_pk_fma_f32 v[10:11], v[10:11], 0.5, v[152:153] op_sel_hi:[1,0,1]
	v_pk_fma_f32 v[8:9], v[8:9], 0.5, v[150:151] op_sel_hi:[1,0,1]
	v_cvt_pk_bf16_f32 v136, v12, v13
	v_cvt_pk_bf16_f32 v137, v14, v15
	v_cvt_pk_bf16_f32 v138, v8, v9
	v_cvt_pk_bf16_f32 v139, v10, v11
	global_store_dwordx4 v[238:239], v[136:139], off
	v_mul_f32_e32 v146, v13, v13
	v_mul_f32_e32 v147, v15, v15
	v_fmac_f32_e32 v146, v12, v12
	v_fmac_f32_e32 v147, v14, v14
	v_add_f32_e32 v146, v146, v147
	v_mul_f32_e32 v147, v9, v9
	v_mul_f32_e32 v148, v11, v11
	v_fmac_f32_e32 v147, v8, v8
	v_fmac_f32_e32 v148, v10, v10
	v_add_f32_e32 v147, v147, v148
	v_add_f32_e32 v247, v146, v147
	s_waitcnt vmcnt(15)
	v_lshlrev_b32_e32 v146, 16, v220
	v_and_b32_e32 v147, 0xffff0000, v220
	v_lshlrev_b32_e32 v148, 16, v221
	v_and_b32_e32 v149, 0xffff0000, v221
	v_lshlrev_b32_e32 v150, 16, v222
	v_and_b32_e32 v151, 0xffff0000, v222
	v_lshlrev_b32_e32 v152, 16, v223
	v_and_b32_e32 v153, 0xffff0000, v223
	v_pk_fma_f32 v[6:7], v[6:7], 0.5, v[148:149] op_sel_hi:[1,0,1]
	v_pk_fma_f32 v[4:5], v[4:5], 0.5, v[146:147] op_sel_hi:[1,0,1]
	v_pk_fma_f32 v[2:3], v[2:3], 0.5, v[152:153] op_sel_hi:[1,0,1]
	v_pk_fma_f32 v[0:1], v[0:1], 0.5, v[150:151] op_sel_hi:[1,0,1]
	v_cvt_pk_bf16_f32 v248, v4, v5
	v_cvt_pk_bf16_f32 v249, v6, v7
	v_cvt_pk_bf16_f32 v250, v0, v1
	v_cvt_pk_bf16_f32 v251, v2, v3
	global_store_dwordx4 v[238:239], v[248:251], off offset:256
	v_mul_f32_e32 v146, v5, v5
	v_mul_f32_e32 v147, v7, v7
	v_fmac_f32_e32 v146, v4, v4
	v_fmac_f32_e32 v147, v6, v6
	v_add_f32_e32 v146, v146, v147
	v_mul_f32_e32 v147, v1, v1
	v_mul_f32_e32 v148, v3, v3
	v_fmac_f32_e32 v147, v0, v0
	v_fmac_f32_e32 v148, v2, v2
	v_add_f32_e32 v147, v147, v148
	v_add_f32_e32 v146, v146, v147
	v_add_f32_e32 v247, v247, v146
	ds_bpermute_b32 v154, v145, v240
	ds_bpermute_b32 v155, v145, v241
	ds_bpermute_b32 v156, v145, v242
	ds_bpermute_b32 v157, v145, v243
	ds_bpermute_b32 v158, v145, v244
	ds_bpermute_b32 v159, v145, v245
	ds_bpermute_b32 v160, v145, v246
	ds_bpermute_b32 v161, v145, v247
	s_waitcnt lgkmcnt(7)
	v_add_f32_e32 v240, v240, v154
	ds_bpermute_b32 v154, v144, v240
	s_waitcnt lgkmcnt(7)
	v_add_f32_e32 v241, v241, v155
	ds_bpermute_b32 v155, v144, v241
	s_waitcnt lgkmcnt(7)
	v_add_f32_e32 v242, v242, v156
	ds_bpermute_b32 v156, v144, v242
	s_waitcnt lgkmcnt(7)
	v_add_f32_e32 v243, v243, v157
	ds_bpermute_b32 v157, v144, v243
	s_waitcnt lgkmcnt(7)
	v_add_f32_e32 v244, v244, v158
	ds_bpermute_b32 v158, v144, v244
	s_waitcnt lgkmcnt(7)
	v_add_f32_e32 v245, v245, v159
	ds_bpermute_b32 v159, v144, v245
	s_waitcnt lgkmcnt(7)
	v_add_f32_e32 v246, v246, v160
	ds_bpermute_b32 v160, v144, v246
	s_waitcnt lgkmcnt(7)
	v_add_f32_e32 v247, v247, v161
	ds_bpermute_b32 v161, v144, v247
	s_and_saveexec_b64 s[38:39], vcc
	s_waitcnt lgkmcnt(7)
	v_add_f32_e32 v240, v240, v154
	global_store_dword v[140:141], v240, off
	s_waitcnt lgkmcnt(6)
	v_add_f32_e32 v241, v241, v155
	global_store_dword v[140:141], v241, off offset:1024
	s_waitcnt lgkmcnt(5)
	v_add_f32_e32 v242, v242, v156
	global_store_dword v[140:141], v242, off offset:2048
	s_waitcnt lgkmcnt(4)
	v_add_f32_e32 v243, v243, v157
	global_store_dword v[140:141], v243, off offset:3072
	s_waitcnt lgkmcnt(3)
	v_add_f32_e32 v244, v244, v158
	global_store_dword v[252:253], v244, off
	s_waitcnt lgkmcnt(2)
	v_add_f32_e32 v245, v245, v159
	global_store_dword v[252:253], v245, off offset:1024
	s_waitcnt lgkmcnt(1)
	v_add_f32_e32 v246, v246, v160
	global_store_dword v[252:253], v246, off offset:2048
	s_waitcnt lgkmcnt(0)
	v_add_f32_e32 v247, v247, v161
	global_store_dword v[252:253], v247, off offset:3072
	s_or_b64 exec, exec, s[38:39]
	s_and_b64 vcc, exec, s[6:7]
	s_mov_b64 s[6:7], -1
	s_cbranch_vccnz .LBB0_691
	s_andn2_b64 vcc, exec, s[10:11]
	s_cbranch_vccnz .LBB0_690
	s_barrier
	s_branch .LBB0_690
